# baseline (speedup 1.0000x reference)
; #define WAIT_V(n) asm volatile("s_waitcnt vmcnt(" #n ")" ::: "memory")
; #define BAR __builtin_amdgcn_s_barrier()
; template <int MODE>
; __device__ __forceinline__ void gemm_tile(const int ph, const int which, const int pm, const int pn) {
;     ...
;   STAGE(SB(0, 0), RB, bcol, 0);
;   STAGE(SA(0, 0), RA, brow, 0);
;   STAGE(SB(0, 1), RB, bcolB, 0);
;   STAGE(SA(0, 1), RA, brow + HALF, 0);
;   if (wr == 1) BAR;
;   WAIT_V(4);
;   BAR;
;   STAGE(SB(1, 0), RB, bcol, 1);
;   STAGE(SA(1, 0), RA, brow, 1);
;   STAGE(SB(1, 1), RB, bcolB, 1);
;   WAIT_V(6);
.LBB0_128:
	v_bfe_i32 v3, v0, 27, 1
	v_lshlrev_b32_e32 v139, 4, v0
	v_lshrrev_b32_e32 v3, 22, v3
	v_add_u32_e32 v3, v139, v3
	v_and_b32_e32 v3, 0xfffffc00, v3
	v_ashrrev_i32_e32 v2, 31, v0
	v_sub_u32_e32 v3, v139, v3
	v_lshrrev_b32_e32 v2, 26, v2
	v_lshrrev_b32_e32 v4, 4, v3
	v_add_u32_e32 v2, v0, v2
	v_bitop3_b32 v4, v4, v3, 32 bitop3:0x6c
	v_ashrrev_i32_e32 v3, 31, v3
	v_ashrrev_i32_e32 v2, 6, v2
	v_lshrrev_b32_e32 v3, 26, v3
	v_lshlrev_b32_e32 v5, 3, v2
	v_add_u32_e32 v3, v4, v3
	v_and_b32_e32 v5, 0x7ffffff0, v5
	v_ashrrev_i32_e32 v3, 6, v3
	v_add_u32_e32 v5, v3, v5
	v_mul_i32_i24_e32 v3, 64, v3
	s_add_i32 s24, s6, s3
	v_lshlrev_b32_e32 v2, 5, v2
	v_sub_u32_e32 v3, v4, v3
	s_add_i32 s18, s2, s3
	v_and_b32_e32 v2, 32, v2
	v_ashrrev_i16_sdwa v3, v223, sext(v3) dst_sel:DWORD dst_unused:UNUSED_PAD src0_sel:DWORD src1_sel:BYTE_0
	s_mul_i32 s2, s24, s26
	v_add_u32_e32 v141, 0x10000, v139
	v_add_u32_sdwa v2, v2, sext(v3) dst_sel:DWORD dst_unused:UNUSED_PAD src0_sel:DWORD src1_sel:WORD_0
	v_mul_lo_u32 v3, s26, v5
	s_lshl_b32 s19, s2, 1
	v_readfirstlane_b32 s2, v141
	v_add_u32_e32 v142, 0x12000, v139
	s_and_b32 s69, s69, 0xffff
	v_add_lshl_u32 v138, v2, v3, 1
	s_mov_b32 m0, s2
	s_lshl_b32 s10, s26, 7
	v_readfirstlane_b32 s3, v142
	buffer_load_dwordx4 v138, s[68:71], s19 offen lds
	s_add_i32 s2, s19, s10
	s_mov_b32 m0, s3
	s_mul_i32 s11, s22, s26
	buffer_load_dwordx4 v138, s[68:71], s2 offen lds
	v_readfirstlane_b32 s2, v139
	v_add_u32_e32 v143, 0x2000, v139
	s_and_b32 s5, s5, 0xffff
	s_mov_b32 s6, s70
	s_mov_b32 s7, s71
	s_lshl_b32 s17, s11, 1
	s_mov_b32 m0, s2
	v_readfirstlane_b32 s3, v143
	buffer_load_dwordx4 v138, s[4:7], s17 offen lds
	s_add_i32 s2, s17, s10
	s_mov_b32 m0, s3
	v_add_u32_e32 v144, 0x14000, v139
	buffer_load_dwordx4 v138, s[4:7], s2 offen lds
	s_mul_i32 s2, s18, s26
	s_lshl_b32 s16, s2, 1
	v_readfirstlane_b32 s2, v144
	v_add_u32_e32 v145, 0x16000, v139
	s_mov_b32 m0, s2
	v_readfirstlane_b32 s3, v145
	v_add_u32_e32 v147, 0x4000, v139
	buffer_load_dwordx4 v138, s[68:71], s16 offen lds
	s_add_i32 s2, s16, s10
	s_mov_b32 m0, s3
	s_add_i32 s11, s11, s10
	v_readfirstlane_b32 s3, v147
	v_add_u32_e32 v148, 0x6000, v139
	buffer_load_dwordx4 v138, s[68:71], s2 offen lds
	s_lshl_b32 s2, s11, 1
	s_mov_b32 m0, s3
	v_readfirstlane_b32 s3, v148
	buffer_load_dwordx4 v138, s[4:7], s2 offen lds
	s_add_i32 s2, s2, s10
	s_mov_b32 m0, s3
	v_ashrrev_i32_e32 v2, 8, v0
	buffer_load_dwordx4 v138, s[4:7], s2 offen lds
	v_add_u32_e32 v149, 0x18000, v139
	v_add_u32_e32 v150, 0x1a000, v139
	v_readfirstlane_b32 s6, v149
	s_or_b32 s3, s19, 0x80
	s_mov_b32 m0, s6
	v_readfirstlane_b32 s6, v150
	v_add_u32_e32 v151, 0x8000, v139
	buffer_load_dwordx4 v138, s[68:71], s3 offen lds
	s_add_i32 s3, s3, s10
	s_mov_b32 m0, s6
	v_readfirstlane_b32 s12, v151
	v_add_u32_e32 v152, 0xa000, v139
	buffer_load_dwordx4 v138, s[68:71], s3 offen lds
	s_or_b32 s3, s17, 0x80
	s_mov_b32 s6, s70
	s_mov_b32 s7, s71
	s_mov_b32 m0, s12
	v_readfirstlane_b32 s12, v152
	v_add_u32_e32 v154, 0x1c000, v139
	buffer_load_dwordx4 v138, s[4:7], s3 offen lds
	s_add_i32 s3, s3, s10
	s_mov_b32 m0, s12
	v_readfirstlane_b32 s12, v154
	v_add_u32_e32 v156, 0x1e000, v139
	buffer_load_dwordx4 v138, s[4:7], s3 offen lds
	s_or_b32 s3, s16, 0x80
	s_mov_b32 m0, s12
	v_readfirstlane_b32 s12, v156
	buffer_load_dwordx4 v138, s[68:71], s3 offen lds
	s_add_i32 s3, s3, s10
	s_mov_b32 m0, s12
	v_and_b32_e32 v3, 15, v0
	buffer_load_dwordx4 v138, s[68:71], s3 offen lds
	v_cmp_eq_u32_e32 vcc, 1, v2
	s_and_saveexec_b64 s[98:99], vcc
	s_cbranch_execz .LBB0_130
	s_barrier
; #define WAIT_V(n) asm volatile("s_waitcnt vmcnt(" #n ")" ::: "memory")
; #define BAR __builtin_amdgcn_s_barrier()
; template <int MODE>
; __device__ __forceinline__ void gemm_tile(const int ph, const int which, const int pm, const int pn) {
;     ...
;   f32x4 acc[2][2][4][2] = {};
;   bf16x8 At[4][2], B0[2][2], B1[2][2];
;   const int nt = K / BK;
;     ...
;   if (wr == 1) BAR;
;   WAIT_V(4);
;   BAR;
;   STAGE(SB(1, 0), RB, bcol, 1);
;   STAGE(SA(1, 0), RA, brow, 1);
;   STAGE(SB(1, 1), RB, bcolB, 1);
;   WAIT_V(6);
;   BAR;
.LBB0_130:
	s_or_b64 exec, exec, s[98:99]
	s_waitcnt vmcnt(10)
	s_barrier
	v_bfe_u32 v132, v0, 4, 2
	v_lshlrev_b32_e32 v5, 4, v132
	v_lshlrev_b32_e32 v6, 6, v3
	v_lshlrev_b32_e32 v8, 2, v0
	v_or_b32_e32 v7, v5, v6
	v_and_b32_e32 v8, 32, v8
	s_mov_b32 s3, 0x10000
	v_bitop3_b32 v9, v7, s3, v8 bitop3:0xde
	s_mov_b32 s3, 0x14000
	v_bitop3_b32 v10, v7, s3, v8 bitop3:0xde
	s_mov_b32 s3, 0x18000
	v_bitop3_b32 v11, v7, s3, v8 bitop3:0xde
	s_mov_b32 s3, 0x1c000
	s_lshl_b32 s12, s22, 1
	v_bitop3_b32 v7, v7, s3, v8 bitop3:0xde
	v_lshl_or_b32 v133, v2, 6, v3
	v_lshlrev_b32_e32 v3, 13, v2
	v_lshlrev_b32_e32 v2, 6, v0
	s_add_i32 s3, s12, 0x180
	s_addk_i32 s12, 0x80
	v_bfe_u32 v131, v0, 6, 2
	v_and_b32_e32 v2, 0x3c0, v2
	s_lshl_b32 s17, s18, 1
	s_mul_i32 s19, s26, s12
	s_lshl_b32 s12, s24, 1
	s_lshr_b32 s2, s26, 6
	v_lshlrev_b32_e32 v4, 12, v131
	v_bitop3_b32 v6, v5, v8, v6 bitop3:0x36
	v_bitop3_b32 v5, v2, v8, v5 bitop3:0x36
	v_or_b32_e32 v8, 0x800, v3
	v_or_b32_e32 v12, 0x1000, v3
	v_or_b32_e32 v13, 0x1800, v3
	s_lshl_b32 s13, s26, 1
	s_add_i32 s16, s22, 0x80
	s_addk_i32 s17, 0x80
	s_addk_i32 s12, 0x80
	v_mov_b32_e32 v2, 0
	v_lshrrev_b32_e32 v130, 4, v0
	s_add_i32 s2, s2, -2
	v_add_u32_e32 v155, 0xc000, v139
	v_add_u32_e32 v153, 0xe000, v139
	s_mul_i32 s3, s26, s3
	s_mul_i32 s16, s13, s16
	s_mul_i32 s17, s26, s17
	s_mul_i32 s18, s13, s18
	s_mul_i32 s22, s13, s22
	s_mul_i32 s23, s26, s12
	s_mul_i32 s24, s13, s24
	s_mov_b32 s25, 0
	v_add_u32_e32 v158, v9, v4
	v_add_u32_e32 v137, v6, v3
	v_add_u32_e32 v136, v5, v8
	v_add_u32_e32 v135, v5, v12
	v_add_u32_e32 v134, v5, v13
	v_add_u32_e32 v157, v10, v4
	v_add_u32_e32 v146, v11, v4
	v_add_u32_e32 v140, v7, v4
	s_mov_b32 s27, 0
	v_mov_b32_e32 v3, v2
	v_mov_b32_e32 v4, v2
	v_mov_b32_e32 v5, v2
	v_mov_b32_e32 v6, v2
	v_mov_b32_e32 v7, v2
	v_mov_b32_e32 v8, v2
	v_mov_b32_e32 v9, v2
	v_mov_b32_e32 v10, v2
	v_mov_b32_e32 v11, v2
	v_mov_b32_e32 v12, v2
	v_mov_b32_e32 v13, v2
	v_mov_b32_e32 v14, v2
	v_mov_b32_e32 v15, v2
	v_mov_b32_e32 v16, v2
	v_mov_b32_e32 v17, v2
	v_mov_b32_e32 v18, v2
	v_mov_b32_e32 v19, v2
	v_mov_b32_e32 v20, v2
	v_mov_b32_e32 v21, v2
	v_mov_b32_e32 v22, v2
	v_mov_b32_e32 v23, v2
	v_mov_b32_e32 v24, v2
	v_mov_b32_e32 v25, v2
	v_mov_b32_e32 v26, v2
	v_mov_b32_e32 v27, v2
	v_mov_b32_e32 v28, v2
	v_mov_b32_e32 v29, v2
	v_mov_b32_e32 v30, v2
	v_mov_b32_e32 v31, v2
	v_mov_b32_e32 v32, v2
	v_mov_b32_e32 v33, v2
	v_mov_b32_e32 v34, v2
	v_mov_b32_e32 v35, v2
	v_mov_b32_e32 v36, v2
	v_mov_b32_e32 v37, v2
	v_mov_b32_e32 v38, v2
	v_mov_b32_e32 v39, v2
	v_mov_b32_e32 v40, v2
	v_mov_b32_e32 v41, v2
	v_mov_b32_e32 v42, v2
	v_mov_b32_e32 v43, v2
	v_mov_b32_e32 v44, v2
	v_mov_b32_e32 v45, v2
	v_mov_b32_e32 v46, v2
	v_mov_b32_e32 v47, v2
	v_mov_b32_e32 v48, v2
	v_mov_b32_e32 v49, v2
	v_mov_b32_e32 v50, v2
	v_mov_b32_e32 v51, v2
	v_mov_b32_e32 v52, v2
	v_mov_b32_e32 v53, v2
	v_mov_b32_e32 v54, v2
	v_mov_b32_e32 v55, v2
	v_mov_b32_e32 v56, v2
	v_mov_b32_e32 v57, v2
	v_mov_b32_e32 v58, v2
	v_mov_b32_e32 v59, v2
	v_mov_b32_e32 v60, v2
	v_mov_b32_e32 v61, v2
	v_mov_b32_e32 v62, v2
	v_mov_b32_e32 v63, v2
	v_mov_b32_e32 v64, v2
	v_mov_b32_e32 v65, v2
	v_mov_b32_e32 v66, v2
	v_mov_b32_e32 v67, v2
	v_mov_b32_e32 v68, v2
	v_mov_b32_e32 v69, v2
	v_mov_b32_e32 v70, v2
	v_mov_b32_e32 v71, v2
	v_mov_b32_e32 v72, v2
	v_mov_b32_e32 v73, v2
	v_mov_b32_e32 v74, v2
	v_mov_b32_e32 v75, v2
	v_mov_b32_e32 v76, v2
	v_mov_b32_e32 v77, v2
	v_mov_b32_e32 v78, v2
	v_mov_b32_e32 v79, v2
	v_mov_b32_e32 v80, v2
	v_mov_b32_e32 v81, v2
	v_mov_b32_e32 v82, v2
	v_mov_b32_e32 v83, v2
	v_mov_b32_e32 v84, v2
	v_mov_b32_e32 v85, v2
	v_mov_b32_e32 v86, v2
	v_mov_b32_e32 v87, v2
	v_mov_b32_e32 v88, v2
	v_mov_b32_e32 v89, v2
	v_mov_b32_e32 v90, v2
	v_mov_b32_e32 v91, v2
	v_mov_b32_e32 v92, v2
	v_mov_b32_e32 v93, v2
	v_mov_b32_e32 v94, v2
	v_mov_b32_e32 v95, v2
	v_mov_b32_e32 v96, v2
	v_mov_b32_e32 v97, v2
	v_mov_b32_e32 v98, v2
	v_mov_b32_e32 v99, v2
	v_mov_b32_e32 v100, v2
	v_mov_b32_e32 v101, v2
	v_mov_b32_e32 v102, v2
	v_mov_b32_e32 v103, v2
	v_mov_b32_e32 v104, v2
	v_mov_b32_e32 v105, v2
	v_mov_b32_e32 v106, v2
	v_mov_b32_e32 v107, v2
	v_mov_b32_e32 v108, v2
	v_mov_b32_e32 v109, v2
	v_mov_b32_e32 v110, v2
	v_mov_b32_e32 v111, v2
	v_mov_b32_e32 v112, v2
	v_mov_b32_e32 v113, v2
	v_mov_b32_e32 v114, v2
	v_mov_b32_e32 v115, v2
	v_mov_b32_e32 v116, v2
	v_mov_b32_e32 v117, v2
	v_mov_b32_e32 v118, v2
	v_mov_b32_e32 v119, v2
	v_mov_b32_e32 v120, v2
	v_mov_b32_e32 v121, v2
	v_mov_b32_e32 v122, v2
	v_mov_b32_e32 v123, v2
	v_mov_b32_e32 v124, v2
	v_mov_b32_e32 v125, v2
	v_mov_b32_e32 v126, v2
	v_mov_b32_e32 v127, v2
	v_mov_b32_e32 v128, v2
	v_mov_b32_e32 v129, v2
	s_waitcnt vmcnt(6)

; #define WAIT_V(n) asm volatile("s_waitcnt vmcnt(" #n ")" ::: "memory")
; #define BAR __builtin_amdgcn_s_barrier()
; template <int MODE>
; __device__ __forceinline__ void gemm_tile(const int ph, const int which, const int pm, const int pn) {
;     ...
;   STAGE(SB(0, 0), RB, bcol, 0);
;   STAGE(SA(0, 0), RA, brow, 0);
;   STAGE(SB(0, 1), RB, bcolB, 0);
;   STAGE(SA(0, 1), RA, brow + HALF, 0);
;   if (wr == 1) BAR;
;   WAIT_V(4);
;   BAR;
;   STAGE(SB(1, 0), RB, bcol, 1);
;   STAGE(SA(1, 0), RA, brow, 1);
;   STAGE(SB(1, 1), RB, bcolB, 1);
;   WAIT_V(6);
.LBB0_215:
	v_bfe_i32 v3, v0, 27, 1
	v_lshlrev_b32_e32 v136, 4, v0
	v_lshrrev_b32_e32 v3, 22, v3
	v_add_u32_e32 v3, v136, v3
	v_and_b32_e32 v3, 0xfffffc00, v3
	v_ashrrev_i32_e32 v2, 31, v0
	v_sub_u32_e32 v3, v136, v3
	v_lshrrev_b32_e32 v2, 26, v2
	v_lshrrev_b32_e32 v4, 4, v3
	v_add_u32_e32 v2, v0, v2
	v_bitop3_b32 v4, v4, v3, 32 bitop3:0x6c
	v_ashrrev_i32_e32 v3, 31, v3
	v_ashrrev_i32_e32 v2, 6, v2
	v_lshrrev_b32_e32 v3, 26, v3
	v_lshlrev_b32_e32 v5, 3, v2
	v_add_u32_e32 v3, v4, v3
	v_and_b32_e32 v5, 0x7ffffff0, v5
	v_ashrrev_i32_e32 v3, 6, v3
	v_add_u32_e32 v5, v3, v5
	v_mul_i32_i24_e32 v3, 64, v3
	s_add_i32 s26, s10, s7
	v_lshlrev_b32_e32 v2, 5, v2
	v_sub_u32_e32 v3, v4, v3
	v_and_b32_e32 v2, 32, v2
	v_ashrrev_i16_sdwa v3, v223, sext(v3) dst_sel:DWORD dst_unused:UNUSED_PAD src0_sel:DWORD src1_sel:BYTE_0
	s_mul_i32 s10, s26, s28
	v_add_u32_e32 v139, 0x10000, v136
	v_add_u32_sdwa v2, v2, sext(v3) dst_sel:DWORD dst_unused:UNUSED_PAD src0_sel:DWORD src1_sel:WORD_0
	v_mul_lo_u32 v3, s28, v5
	s_lshl_b32 s18, s10, 1
	v_readfirstlane_b32 s10, v139
	v_add_u32_e32 v140, 0x12000, v136
	s_and_b32 s69, s69, 0xffff
	v_add_lshl_u32 v135, v2, v3, 1
	s_mov_b32 m0, s10
	s_lshl_b32 s10, s28, 7
	v_readfirstlane_b32 s12, v140
	buffer_load_dwordx4 v135, s[68:71], s18 offen lds
	s_add_i32 s11, s18, s10
	s_mov_b32 m0, s12
	v_readfirstlane_b32 s12, v136
	buffer_load_dwordx4 v135, s[68:71], s11 offen lds
	s_mul_i32 s11, s22, s28
	v_add_u32_e32 v141, 0x2000, v136
	s_add_i32 s20, s6, s7
	s_and_b32 s5, s5, 0xffff
	s_mov_b32 s6, s70
	s_mov_b32 s7, s71
	s_lshl_b32 s17, s11, 1
	s_mov_b32 m0, s12
	v_readfirstlane_b32 s13, v141
	buffer_load_dwordx4 v135, s[4:7], s17 offen lds
	s_add_i32 s12, s17, s10
	s_mov_b32 m0, s13
	v_add_u32_e32 v142, 0x14000, v136
	buffer_load_dwordx4 v135, s[4:7], s12 offen lds
	s_mul_i32 s12, s20, s28
	s_lshl_b32 s16, s12, 1
	v_readfirstlane_b32 s12, v142
	v_add_u32_e32 v143, 0x16000, v136
	s_mov_b32 m0, s12
	v_readfirstlane_b32 s13, v143
	v_add_u32_e32 v145, 0x4000, v136
	buffer_load_dwordx4 v135, s[68:71], s16 offen lds
	s_add_i32 s12, s16, s10
	s_mov_b32 m0, s13
	s_add_i32 s11, s11, s10
	v_readfirstlane_b32 s13, v145
	v_add_u32_e32 v146, 0x6000, v136
	buffer_load_dwordx4 v135, s[68:71], s12 offen lds
	s_lshl_b32 s12, s11, 1
	s_mov_b32 m0, s13
	v_readfirstlane_b32 s13, v146
	buffer_load_dwordx4 v135, s[4:7], s12 offen lds
	s_add_i32 s12, s12, s10
	s_mov_b32 m0, s13
	v_ashrrev_i32_e32 v2, 8, v0
	buffer_load_dwordx4 v135, s[4:7], s12 offen lds
	v_add_u32_e32 v147, 0x18000, v136
	v_add_u32_e32 v148, 0x1a000, v136
	v_readfirstlane_b32 s7, v147
	s_or_b32 s6, s18, 0x80
	s_mov_b32 m0, s7
	v_readfirstlane_b32 s7, v148
	v_add_u32_e32 v149, 0x8000, v136
	buffer_load_dwordx4 v135, s[68:71], s6 offen lds
	s_add_i32 s6, s6, s10
	s_mov_b32 m0, s7
	s_or_b32 s13, s17, 0x80
	v_readfirstlane_b32 s17, v149
	v_add_u32_e32 v150, 0xa000, v136
	buffer_load_dwordx4 v135, s[68:71], s6 offen lds
	s_mov_b32 s6, s70
	s_mov_b32 s7, s71
	s_mov_b32 m0, s17
	v_readfirstlane_b32 s17, v150
	buffer_load_dwordx4 v135, s[4:7], s13 offen lds
	s_add_i32 s13, s13, s10
	s_mov_b32 m0, s17
	v_add_u32_e32 v152, 0x1c000, v136
	buffer_load_dwordx4 v135, s[4:7], s13 offen lds
	s_or_b32 s13, s16, 0x80
	v_readfirstlane_b32 s16, v152
	v_add_u32_e32 v154, 0x1e000, v136
	s_mov_b32 m0, s16
	v_readfirstlane_b32 s16, v154
	buffer_load_dwordx4 v135, s[68:71], s13 offen lds
	s_add_i32 s13, s13, s10
	s_mov_b32 m0, s16
	v_and_b32_e32 v3, 15, v0
	buffer_load_dwordx4 v135, s[68:71], s13 offen lds
	v_cmp_eq_u32_e32 vcc, 1, v2
	s_and_saveexec_b64 s[98:99], vcc
	s_cbranch_execz .LBB0_217
	s_barrier
; #define WAIT_V(n) asm volatile("s_waitcnt vmcnt(" #n ")" ::: "memory")
; #define BAR __builtin_amdgcn_s_barrier()
; template <int MODE>
; __device__ __forceinline__ void gemm_tile(const int ph, const int which, const int pm, const int pn) {
;     ...
;   f32x4 acc[2][2][4][2] = {};
;   bf16x8 At[4][2], B0[2][2], B1[2][2];
;   const int nt = K / BK;
;     ...
;   if (wr == 1) BAR;
;   WAIT_V(4);
;   BAR;
;   STAGE(SB(1, 0), RB, bcol, 1);
;   STAGE(SA(1, 0), RA, brow, 1);
;   STAGE(SB(1, 1), RB, bcolB, 1);
;   WAIT_V(6);
;   BAR;
.LBB0_217:
	s_or_b64 exec, exec, s[98:99]
	s_waitcnt vmcnt(10)
	s_barrier
	s_lshr_b32 s12, s28, 6
	v_and_b32_e32 v5, 48, v0
	v_lshlrev_b32_e32 v6, 6, v3
	v_lshlrev_b32_e32 v8, 2, v0
	s_add_i32 s16, s12, -2
	v_or_b32_e32 v7, v6, v5
	v_and_b32_e32 v8, 32, v8
	s_mov_b32 s12, 0x10000
	v_bitop3_b32 v9, v7, s12, v8 bitop3:0xde
	s_mov_b32 s12, 0x14000
	v_bitop3_b32 v10, v7, s12, v8 bitop3:0xde
	s_mov_b32 s12, 0x18000
	v_bitop3_b32 v11, v7, s12, v8 bitop3:0xde
	s_mov_b32 s12, 0x1c000
	v_bitop3_b32 v7, v7, s12, v8 bitop3:0xde
	s_lshl_b32 s12, s22, 1
	v_lshl_or_b32 v130, v2, 6, v3
	v_lshlrev_b32_e32 v3, 13, v2
	v_lshlrev_b32_e32 v2, 6, v0
	s_add_i32 s13, s12, 0x180
	s_addk_i32 s12, 0x80
	v_bfe_u32 v138, v0, 6, 2
	v_and_b32_e32 v2, 0x3c0, v2
	s_lshl_b32 s19, s20, 1
	s_mul_i32 s21, s28, s12
	s_lshl_b32 s12, s26, 1
	v_lshlrev_b32_e32 v4, 12, v138
	v_bitop3_b32 v6, v6, v8, v5 bitop3:0x36
	v_bitop3_b32 v5, v2, v8, v5 bitop3:0x36
	v_or_b32_e32 v8, 0x800, v3
	v_or_b32_e32 v12, 0x1000, v3
	v_or_b32_e32 v13, 0x1800, v3
	s_mul_i32 s17, s28, s13
	s_lshl_b32 s13, s28, 1
	s_add_i32 s18, s22, 0x80
	s_addk_i32 s19, 0x80
	s_addk_i32 s12, 0x80
	v_mov_b32_e32 v2, 0
	v_add_u32_e32 v153, 0xc000, v136
	v_add_u32_e32 v151, 0xe000, v136
	s_mul_i32 s18, s13, s18
	s_mul_i32 s19, s28, s19
	s_mul_i32 s20, s13, s20
	s_mul_i32 s22, s13, s22
	s_mul_i32 s25, s28, s12
	s_mul_i32 s26, s13, s26
	s_mov_b32 s27, 0
	v_add_u32_e32 v156, v9, v4
	v_add_u32_e32 v134, v6, v3
	v_add_u32_e32 v133, v5, v8
	v_add_u32_e32 v132, v5, v12
	v_add_u32_e32 v131, v5, v13
	v_add_u32_e32 v155, v10, v4
	v_add_u32_e32 v144, v11, v4
	v_add_u32_e32 v137, v7, v4
	s_mov_b32 vcc_lo, 0
	v_mov_b32_e32 v3, v2
	v_mov_b32_e32 v4, v2
	v_mov_b32_e32 v5, v2
	v_mov_b32_e32 v6, v2
	v_mov_b32_e32 v7, v2
	v_mov_b32_e32 v8, v2
	v_mov_b32_e32 v9, v2
	v_mov_b32_e32 v10, v2
	v_mov_b32_e32 v11, v2
	v_mov_b32_e32 v12, v2
	v_mov_b32_e32 v13, v2
	v_mov_b32_e32 v14, v2
	v_mov_b32_e32 v15, v2
	v_mov_b32_e32 v16, v2
	v_mov_b32_e32 v17, v2
	v_mov_b32_e32 v18, v2
	v_mov_b32_e32 v19, v2
	v_mov_b32_e32 v20, v2
	v_mov_b32_e32 v21, v2
	v_mov_b32_e32 v22, v2
	v_mov_b32_e32 v23, v2
	v_mov_b32_e32 v24, v2
	v_mov_b32_e32 v25, v2
	v_mov_b32_e32 v26, v2
	v_mov_b32_e32 v27, v2
	v_mov_b32_e32 v28, v2
	v_mov_b32_e32 v29, v2
	v_mov_b32_e32 v30, v2
	v_mov_b32_e32 v31, v2
	v_mov_b32_e32 v32, v2
	v_mov_b32_e32 v33, v2
	v_mov_b32_e32 v34, v2
	v_mov_b32_e32 v35, v2
	v_mov_b32_e32 v36, v2
	v_mov_b32_e32 v37, v2
	v_mov_b32_e32 v38, v2
	v_mov_b32_e32 v39, v2
	v_mov_b32_e32 v40, v2
	v_mov_b32_e32 v41, v2
	v_mov_b32_e32 v42, v2
	v_mov_b32_e32 v43, v2
	v_mov_b32_e32 v44, v2
	v_mov_b32_e32 v45, v2
	v_mov_b32_e32 v46, v2
	v_mov_b32_e32 v47, v2
	v_mov_b32_e32 v48, v2
	v_mov_b32_e32 v49, v2
	v_mov_b32_e32 v50, v2
	v_mov_b32_e32 v51, v2
	v_mov_b32_e32 v52, v2
	v_mov_b32_e32 v53, v2
	v_mov_b32_e32 v54, v2
	v_mov_b32_e32 v55, v2
	v_mov_b32_e32 v56, v2
	v_mov_b32_e32 v57, v2
	v_mov_b32_e32 v58, v2
	v_mov_b32_e32 v59, v2
	v_mov_b32_e32 v60, v2
	v_mov_b32_e32 v61, v2
	v_mov_b32_e32 v62, v2
	v_mov_b32_e32 v63, v2
	v_mov_b32_e32 v64, v2
	v_mov_b32_e32 v65, v2
	v_mov_b32_e32 v66, v2
	v_mov_b32_e32 v67, v2
	v_mov_b32_e32 v68, v2
	v_mov_b32_e32 v69, v2
	v_mov_b32_e32 v70, v2
	v_mov_b32_e32 v71, v2
	v_mov_b32_e32 v72, v2
	v_mov_b32_e32 v73, v2
	v_mov_b32_e32 v74, v2
	v_mov_b32_e32 v75, v2
	v_mov_b32_e32 v76, v2
	v_mov_b32_e32 v77, v2
	v_mov_b32_e32 v78, v2
	v_mov_b32_e32 v79, v2
	v_mov_b32_e32 v80, v2
	v_mov_b32_e32 v81, v2
	v_mov_b32_e32 v82, v2
	v_mov_b32_e32 v83, v2
	v_mov_b32_e32 v84, v2
	v_mov_b32_e32 v85, v2
	v_mov_b32_e32 v86, v2
	v_mov_b32_e32 v87, v2
	v_mov_b32_e32 v88, v2
	v_mov_b32_e32 v89, v2
	v_mov_b32_e32 v90, v2
	v_mov_b32_e32 v91, v2
	v_mov_b32_e32 v92, v2
	v_mov_b32_e32 v93, v2
	v_mov_b32_e32 v94, v2
	v_mov_b32_e32 v95, v2
	v_mov_b32_e32 v96, v2
	v_mov_b32_e32 v97, v2
	v_mov_b32_e32 v98, v2
	v_mov_b32_e32 v99, v2
	v_mov_b32_e32 v100, v2
	v_mov_b32_e32 v101, v2
	v_mov_b32_e32 v102, v2
	v_mov_b32_e32 v103, v2
	v_mov_b32_e32 v104, v2
	v_mov_b32_e32 v105, v2
	v_mov_b32_e32 v106, v2
	v_mov_b32_e32 v107, v2
	v_mov_b32_e32 v108, v2
	v_mov_b32_e32 v109, v2
	v_mov_b32_e32 v110, v2
	v_mov_b32_e32 v111, v2
	v_mov_b32_e32 v112, v2
	v_mov_b32_e32 v113, v2
	v_mov_b32_e32 v114, v2
	v_mov_b32_e32 v115, v2
	v_mov_b32_e32 v116, v2
	v_mov_b32_e32 v117, v2
	v_mov_b32_e32 v118, v2
	v_mov_b32_e32 v119, v2
	v_mov_b32_e32 v120, v2
	v_mov_b32_e32 v121, v2
	v_mov_b32_e32 v122, v2
	v_mov_b32_e32 v123, v2
	v_mov_b32_e32 v124, v2
	v_mov_b32_e32 v125, v2
	v_mov_b32_e32 v126, v2
	v_mov_b32_e32 v127, v2
	v_mov_b32_e32 v128, v2
	v_mov_b32_e32 v129, v2
	s_waitcnt vmcnt(6)

; #define WAIT_V(n) asm volatile("s_waitcnt vmcnt(" #n ")" ::: "memory")
; #define BAR __builtin_amdgcn_s_barrier()
; template <int MODE>
; __device__ __forceinline__ void gemm_tile(const int ph, const int which, const int pm, const int pn) {
;     ...
;   STAGE(SB(0, 0), RB, bcol, 0);
;   STAGE(SA(0, 0), RA, brow, 0);
;   STAGE(SB(0, 1), RB, bcolB, 0);
;   STAGE(SA(0, 1), RA, brow + HALF, 0);
;   if (wr == 1) BAR;
;   WAIT_V(4);
;   BAR;
;   STAGE(SB(1, 0), RB, bcol, 1);
;   STAGE(SA(1, 0), RA, brow, 1);
;   STAGE(SB(1, 1), RB, bcolB, 1);
;   WAIT_V(6);
.LBB0_367:
	v_bfe_i32 v2, v164, 27, 1
	v_lshlrev_b32_e32 v131, 4, v164
	v_lshrrev_b32_e32 v2, 22, v2
	v_add_u32_e32 v2, v131, v2
	v_and_b32_e32 v2, 0xfffffc00, v2
	v_ashrrev_i32_e32 v0, 31, v164
	v_sub_u32_e32 v2, v131, v2
	v_lshrrev_b32_e32 v0, 26, v0
	v_lshrrev_b32_e32 v3, 4, v2
	v_add_u32_e32 v0, v164, v0
	v_bitop3_b32 v3, v3, v2, 32 bitop3:0x6c
	v_ashrrev_i32_e32 v2, 31, v2
	v_ashrrev_i32_e32 v0, 6, v0
	v_lshrrev_b32_e32 v2, 26, v2
	v_lshlrev_b32_e32 v4, 3, v0
	v_add_u32_e32 v2, v3, v2
	v_and_b32_e32 v4, 0x7ffffff0, v4
	v_ashrrev_i32_e32 v2, 6, v2
	v_add_u32_e32 v4, v2, v4
	v_mul_i32_i24_e32 v2, 64, v2
	s_add_i32 s20, s6, s3
	v_lshlrev_b32_e32 v0, 5, v0
	v_sub_u32_e32 v2, v3, v2
	s_add_i32 s16, s2, s3
	v_and_b32_e32 v0, 32, v0
	v_ashrrev_i16_sdwa v2, v223, sext(v2) dst_sel:DWORD dst_unused:UNUSED_PAD src0_sel:DWORD src1_sel:BYTE_0
	s_mul_i32 s2, s20, s26
	v_add_u32_e32 v132, 0x10000, v131
	v_add_u32_sdwa v0, v0, sext(v2) dst_sel:DWORD dst_unused:UNUSED_PAD src0_sel:DWORD src1_sel:WORD_0
	v_mul_lo_u32 v2, s26, v4
	s_lshl_b32 s17, s2, 1
	v_readfirstlane_b32 s2, v132
	v_add_u32_e32 v133, 0x12000, v131
	s_and_b32 s69, s69, 0xffff
	v_add_lshl_u32 v130, v0, v2, 1
	s_mov_b32 m0, s2
	s_lshl_b32 s8, s26, 7
	v_readfirstlane_b32 s3, v133
	buffer_load_dwordx4 v130, s[68:71], s17 offen lds
	s_add_i32 s2, s17, s8
	s_mov_b32 m0, s3
	s_mul_i32 s9, s18, s26
	buffer_load_dwordx4 v130, s[68:71], s2 offen lds
	v_readfirstlane_b32 s2, v131
	v_add_u32_e32 v134, 0x2000, v131
	s_and_b32 s5, s5, 0xffff
	s_mov_b32 s6, s70
	s_mov_b32 s7, s71
	s_lshl_b32 s11, s9, 1
	s_mov_b32 m0, s2
	v_readfirstlane_b32 s3, v134
	buffer_load_dwordx4 v130, s[4:7], s11 offen lds
	s_add_i32 s2, s11, s8
	s_mov_b32 m0, s3
	v_add_u32_e32 v135, 0x14000, v131
	buffer_load_dwordx4 v130, s[4:7], s2 offen lds
	s_mul_i32 s2, s16, s26
	s_lshl_b32 s10, s2, 1
	v_readfirstlane_b32 s2, v135
	v_add_u32_e32 v136, 0x16000, v131
	s_mov_b32 m0, s2
	v_readfirstlane_b32 s3, v136
	v_add_u32_e32 v143, 0x4000, v131
	buffer_load_dwordx4 v130, s[68:71], s10 offen lds
	s_add_i32 s2, s10, s8
	s_mov_b32 m0, s3
	s_add_i32 s9, s9, s8
	v_readfirstlane_b32 s3, v143
	v_add_u32_e32 v144, 0x6000, v131
	buffer_load_dwordx4 v130, s[68:71], s2 offen lds
	s_lshl_b32 s2, s9, 1
	s_mov_b32 m0, s3
	v_readfirstlane_b32 s3, v144
	buffer_load_dwordx4 v130, s[4:7], s2 offen lds
	s_add_i32 s2, s2, s8
	s_mov_b32 m0, s3
	v_ashrrev_i32_e32 v167, 8, v164
	buffer_load_dwordx4 v130, s[4:7], s2 offen lds
	v_add_u32_e32 v145, 0x18000, v131
	v_add_u32_e32 v146, 0x1a000, v131
	v_readfirstlane_b32 s6, v145
	s_or_b32 s3, s17, 0x80
	s_mov_b32 m0, s6
	v_readfirstlane_b32 s6, v146
	buffer_load_dwordx4 v130, s[68:71], s3 offen lds
	s_add_i32 s3, s3, s8
	s_mov_b32 m0, s6
	v_add_u32_e32 v147, 0x8000, v131
	buffer_load_dwordx4 v130, s[68:71], s3 offen lds
	s_or_b32 s3, s11, 0x80
	v_readfirstlane_b32 s11, v147
	v_add_u32_e32 v148, 0xa000, v131
	s_mov_b32 s6, s70
	s_mov_b32 s7, s71
	s_mov_b32 m0, s11
	v_readfirstlane_b32 s11, v148
	buffer_load_dwordx4 v130, s[4:7], s3 offen lds
	s_add_i32 s3, s3, s8
	s_mov_b32 m0, s11
	v_add_u32_e32 v150, 0x1c000, v131
	buffer_load_dwordx4 v130, s[4:7], s3 offen lds
	s_or_b32 s3, s10, 0x80
	v_readfirstlane_b32 s10, v150
	v_add_u32_e32 v152, 0x1e000, v131
	s_mov_b32 m0, s10
	v_readfirstlane_b32 s10, v152
	buffer_load_dwordx4 v130, s[68:71], s3 offen lds
	s_add_i32 s3, s3, s8
	s_mov_b32 m0, s10
	v_and_b32_e32 v2, 15, v164
	buffer_load_dwordx4 v130, s[68:71], s3 offen lds
	v_cmp_eq_u32_e32 vcc, 1, v167
	s_and_saveexec_b64 s[98:99], vcc
	s_cbranch_execz .LBB0_369
	s_barrier
; #define WAIT_V(n) asm volatile("s_waitcnt vmcnt(" #n ")" ::: "memory")
; #define BAR __builtin_amdgcn_s_barrier()
; template <int MODE>
; __device__ __forceinline__ void gemm_tile(const int ph, const int which, const int pm, const int pn) {
;     ...
;   f32x4 acc[2][2][4][2] = {};
;   bf16x8 At[4][2], B0[2][2], B1[2][2];
;   const int nt = K / BK;
;     ...
;   if (wr == 1) BAR;
;   WAIT_V(4);
;   BAR;
;   STAGE(SB(1, 0), RB, bcol, 1);
;   STAGE(SA(1, 0), RA, brow, 1);
;   STAGE(SB(1, 1), RB, bcolB, 1);
;   WAIT_V(6);
;   BAR;
.LBB0_369:
	s_or_b64 exec, exec, s[98:99]
	s_waitcnt vmcnt(10)
	s_barrier
	v_bfe_u32 v162, v164, 4, 2
	v_lshlrev_b32_e32 v4, 4, v162
	v_lshlrev_b32_e32 v5, 6, v2
	v_lshlrev_b32_e32 v7, 2, v164
	v_or_b32_e32 v6, v4, v5
	v_and_b32_e32 v7, 32, v7
	s_mov_b32 s3, 0x10000
	v_bitop3_b32 v8, v6, s3, v7 bitop3:0xde
	s_mov_b32 s3, 0x14000
	v_bitop3_b32 v9, v6, s3, v7 bitop3:0xde
	s_mov_b32 s3, 0x18000
	v_bitop3_b32 v10, v6, s3, v7 bitop3:0xde
	s_mov_b32 s3, 0x1c000
	s_lshl_b32 s12, s18, 1
	v_bitop3_b32 v6, v6, s3, v7 bitop3:0xde
	v_lshl_or_b32 v163, v167, 6, v2
	v_lshlrev_b32_e32 v2, 6, v164
	s_add_i32 s3, s12, 0x180
	s_addk_i32 s12, 0x80
	v_bfe_u32 v0, v164, 6, 2
	v_lshlrev_b32_e32 v11, 13, v167
	v_and_b32_e32 v2, 0x3c0, v2
	s_lshl_b32 s11, s16, 1
	s_mul_i32 s17, s26, s12
	s_lshl_b32 s12, s20, 1
	s_lshr_b32 s2, s26, 6
	v_lshlrev_b32_e32 v3, 12, v0
	v_bitop3_b32 v5, v4, v7, v5 bitop3:0x36
	v_bitop3_b32 v4, v2, v7, v4 bitop3:0x36
	v_or_b32_e32 v7, 0x800, v11
	v_or_b32_e32 v12, 0x1000, v11
	v_or_b32_e32 v13, 0x1800, v11
	s_lshl_b32 s13, s26, 1
	s_add_i32 s10, s18, 0x80
	s_addk_i32 s11, 0x80
	s_addk_i32 s12, 0x80
	v_mov_b32_e32 v2, 0
	s_add_i32 s2, s2, -2
	v_add_u32_e32 v151, 0xc000, v131
	v_add_u32_e32 v149, 0xe000, v131
	s_mul_i32 s3, s26, s3
	s_mul_i32 s10, s13, s10
	s_mul_i32 s11, s26, s11
	s_mul_i32 s16, s13, s16
	s_mul_i32 s18, s13, s18
	s_mul_i32 s19, s26, s12
	s_mul_i32 s20, s13, s20
	s_mov_b32 s21, 0
	v_add_u32_e32 v154, v8, v3
	v_add_u32_e32 v141, v5, v11
	v_add_u32_e32 v140, v4, v7
	v_add_u32_e32 v139, v4, v12
	v_add_u32_e32 v138, v4, v13
	v_add_u32_e32 v153, v9, v3
	v_add_u32_e32 v137, v10, v3
	v_add_u32_e32 v142, v6, v3
	s_mov_b32 s22, 0
	v_mov_b32_e32 v3, v2
	v_mov_b32_e32 v4, v2
	v_mov_b32_e32 v5, v2
	v_mov_b32_e32 v6, v2
	v_mov_b32_e32 v7, v2
	v_mov_b32_e32 v8, v2
	v_mov_b32_e32 v9, v2
	v_mov_b32_e32 v18, v2
	v_mov_b32_e32 v19, v2
	v_mov_b32_e32 v20, v2
	v_mov_b32_e32 v21, v2
	v_mov_b32_e32 v30, v2
	v_mov_b32_e32 v31, v2
	v_mov_b32_e32 v32, v2
	v_mov_b32_e32 v33, v2
	v_mov_b32_e32 v42, v2
	v_mov_b32_e32 v43, v2
	v_mov_b32_e32 v44, v2
	v_mov_b32_e32 v45, v2
	v_mov_b32_e32 v54, v2
	v_mov_b32_e32 v55, v2
	v_mov_b32_e32 v56, v2
	v_mov_b32_e32 v57, v2
	v_mov_b32_e32 v66, v2
	v_mov_b32_e32 v67, v2
	v_mov_b32_e32 v68, v2
	v_mov_b32_e32 v69, v2
	v_mov_b32_e32 v78, v2
	v_mov_b32_e32 v79, v2
	v_mov_b32_e32 v80, v2
	v_mov_b32_e32 v81, v2
	v_mov_b32_e32 v10, v2
	v_mov_b32_e32 v11, v2
	v_mov_b32_e32 v12, v2
	v_mov_b32_e32 v13, v2
	v_mov_b32_e32 v22, v2
	v_mov_b32_e32 v23, v2
	v_mov_b32_e32 v24, v2
	v_mov_b32_e32 v25, v2
	v_mov_b32_e32 v34, v2
	v_mov_b32_e32 v35, v2
	v_mov_b32_e32 v36, v2
	v_mov_b32_e32 v37, v2
	v_mov_b32_e32 v46, v2
	v_mov_b32_e32 v47, v2
	v_mov_b32_e32 v48, v2
	v_mov_b32_e32 v49, v2
	v_mov_b32_e32 v58, v2
	v_mov_b32_e32 v59, v2
	v_mov_b32_e32 v60, v2
	v_mov_b32_e32 v61, v2
	v_mov_b32_e32 v70, v2
	v_mov_b32_e32 v71, v2
	v_mov_b32_e32 v72, v2
	v_mov_b32_e32 v73, v2
	v_mov_b32_e32 v82, v2
	v_mov_b32_e32 v83, v2
	v_mov_b32_e32 v84, v2
	v_mov_b32_e32 v85, v2
	v_mov_b32_e32 v94, v2
	v_mov_b32_e32 v95, v2
	v_mov_b32_e32 v96, v2
	v_mov_b32_e32 v97, v2
	v_mov_b32_e32 v14, v2
	v_mov_b32_e32 v15, v2
	v_mov_b32_e32 v16, v2
	v_mov_b32_e32 v17, v2
	v_mov_b32_e32 v26, v2
	v_mov_b32_e32 v27, v2
	v_mov_b32_e32 v28, v2
	v_mov_b32_e32 v29, v2
	v_mov_b32_e32 v38, v2
	v_mov_b32_e32 v39, v2
	v_mov_b32_e32 v40, v2
	v_mov_b32_e32 v41, v2
	v_mov_b32_e32 v50, v2
	v_mov_b32_e32 v51, v2
	v_mov_b32_e32 v52, v2
	v_mov_b32_e32 v53, v2
	v_mov_b32_e32 v62, v2
	v_mov_b32_e32 v63, v2
	v_mov_b32_e32 v64, v2
	v_mov_b32_e32 v65, v2
	v_mov_b32_e32 v74, v2
	v_mov_b32_e32 v75, v2
	v_mov_b32_e32 v76, v2
	v_mov_b32_e32 v77, v2
	v_mov_b32_e32 v86, v2
	v_mov_b32_e32 v87, v2
	v_mov_b32_e32 v88, v2
	v_mov_b32_e32 v89, v2
	v_mov_b32_e32 v98, v2
	v_mov_b32_e32 v99, v2
	v_mov_b32_e32 v100, v2
	v_mov_b32_e32 v101, v2
	v_mov_b32_e32 v90, v2
	v_mov_b32_e32 v91, v2
	v_mov_b32_e32 v92, v2
	v_mov_b32_e32 v93, v2
	v_mov_b32_e32 v102, v2
	v_mov_b32_e32 v103, v2
	v_mov_b32_e32 v104, v2
	v_mov_b32_e32 v105, v2
	v_mov_b32_e32 v106, v2
	v_mov_b32_e32 v107, v2
	v_mov_b32_e32 v108, v2
	v_mov_b32_e32 v109, v2
	v_mov_b32_e32 v110, v2
	v_mov_b32_e32 v111, v2
	v_mov_b32_e32 v112, v2
	v_mov_b32_e32 v113, v2
	v_mov_b32_e32 v114, v2
	v_mov_b32_e32 v115, v2
	v_mov_b32_e32 v116, v2
	v_mov_b32_e32 v117, v2
	v_mov_b32_e32 v118, v2
	v_mov_b32_e32 v119, v2
	v_mov_b32_e32 v120, v2
	v_mov_b32_e32 v121, v2
	v_mov_b32_e32 v122, v2
	v_mov_b32_e32 v123, v2
	v_mov_b32_e32 v124, v2
	v_mov_b32_e32 v125, v2
	v_mov_b32_e32 v126, v2
	v_mov_b32_e32 v127, v2
	v_mov_b32_e32 v128, v2
	v_mov_b32_e32 v129, v2
	s_waitcnt vmcnt(6)

; #define WAIT_V(n) asm volatile("s_waitcnt vmcnt(" #n ")" ::: "memory")
; #define BAR __builtin_amdgcn_s_barrier()
; template <int MODE>
; __device__ __forceinline__ void gemm_tile(const int ph, const int which, const int pm, const int pn) {
;     ...
;   STAGE(SB(0, 0), RB, bcol, 0);
;   STAGE(SA(0, 0), RA, brow, 0);
;   STAGE(SB(0, 1), RB, bcolB, 0);
;   STAGE(SA(0, 1), RA, brow + HALF, 0);
;   if (wr == 1) BAR;
;   WAIT_V(4);
;   BAR;
;   STAGE(SB(1, 0), RB, bcol, 1);
;   STAGE(SA(1, 0), RA, brow, 1);
;   STAGE(SB(1, 1), RB, bcolB, 1);
;   WAIT_V(6);
.LBB0_537:
	v_bfe_i32 v3, v0, 27, 1
	v_lshlrev_b32_e32 v137, 4, v0
	v_lshrrev_b32_e32 v3, 22, v3
	v_add_u32_e32 v3, v137, v3
	v_and_b32_e32 v3, 0xfffffc00, v3
	v_ashrrev_i32_e32 v2, 31, v0
	v_sub_u32_e32 v3, v137, v3
	v_lshrrev_b32_e32 v2, 26, v2
	v_lshrrev_b32_e32 v4, 4, v3
	v_add_u32_e32 v2, v0, v2
	v_bitop3_b32 v4, v4, v3, 32 bitop3:0x6c
	v_ashrrev_i32_e32 v3, 31, v3
	v_ashrrev_i32_e32 v2, 6, v2
	v_lshrrev_b32_e32 v3, 26, v3
	v_lshlrev_b32_e32 v5, 3, v2
	v_add_u32_e32 v3, v4, v3
	v_and_b32_e32 v5, 0x7ffffff0, v5
	v_ashrrev_i32_e32 v3, 6, v3
	v_add_u32_e32 v5, v3, v5
	v_mul_i32_i24_e32 v3, 64, v3
	s_add_i32 s22, s6, s3
	v_lshlrev_b32_e32 v2, 5, v2
	v_sub_u32_e32 v3, v4, v3
	s_add_i32 s17, s2, s3
	v_and_b32_e32 v2, 32, v2
	v_ashrrev_i16_sdwa v3, v223, sext(v3) dst_sel:DWORD dst_unused:UNUSED_PAD src0_sel:DWORD src1_sel:BYTE_0
	s_mul_i32 s2, s22, s24
	v_add_u32_e32 v139, 0x10000, v137
	v_add_u32_sdwa v2, v2, sext(v3) dst_sel:DWORD dst_unused:UNUSED_PAD src0_sel:DWORD src1_sel:WORD_0
	v_mul_lo_u32 v3, s24, v5
	s_lshl_b32 s19, s2, 1
	v_readfirstlane_b32 s2, v139
	v_add_u32_e32 v140, 0x12000, v137
	s_and_b32 s69, s69, 0xffff
	v_add_lshl_u32 v136, v2, v3, 1
	s_mov_b32 m0, s2
	s_lshl_b32 s8, s24, 7
	v_readfirstlane_b32 s3, v140
	buffer_load_dwordx4 v136, s[68:71], s19 offen lds
	s_add_i32 s2, s19, s8
	s_mov_b32 m0, s3
	s_mul_i32 s9, s20, s24
	buffer_load_dwordx4 v136, s[68:71], s2 offen lds
	v_readfirstlane_b32 s2, v137
	v_add_u32_e32 v141, 0x2000, v137
	s_and_b32 s5, s5, 0xffff
	s_mov_b32 s6, s70
	s_mov_b32 s7, s71
	s_lshl_b32 s11, s9, 1
	s_mov_b32 m0, s2
	v_readfirstlane_b32 s3, v141
	buffer_load_dwordx4 v136, s[4:7], s11 offen lds
	s_add_i32 s2, s11, s8
	s_mov_b32 m0, s3
	v_add_u32_e32 v142, 0x14000, v137
	buffer_load_dwordx4 v136, s[4:7], s2 offen lds
	s_mul_i32 s2, s17, s24
	s_lshl_b32 s10, s2, 1
	v_readfirstlane_b32 s2, v142
	v_add_u32_e32 v143, 0x16000, v137
	s_mov_b32 m0, s2
	v_readfirstlane_b32 s3, v143
	v_add_u32_e32 v145, 0x4000, v137
	buffer_load_dwordx4 v136, s[68:71], s10 offen lds
	s_add_i32 s2, s10, s8
	s_mov_b32 m0, s3
	s_add_i32 s9, s9, s8
	v_readfirstlane_b32 s3, v145
	v_add_u32_e32 v146, 0x6000, v137
	buffer_load_dwordx4 v136, s[68:71], s2 offen lds
	s_lshl_b32 s2, s9, 1
	s_mov_b32 m0, s3
	v_readfirstlane_b32 s3, v146
	buffer_load_dwordx4 v136, s[4:7], s2 offen lds
	s_add_i32 s2, s2, s8
	s_mov_b32 m0, s3
	v_ashrrev_i32_e32 v2, 8, v0
	buffer_load_dwordx4 v136, s[4:7], s2 offen lds
	v_add_u32_e32 v147, 0x18000, v137
	v_add_u32_e32 v148, 0x1a000, v137
	v_readfirstlane_b32 s6, v147
	s_or_b32 s3, s19, 0x80
	s_mov_b32 m0, s6
	v_readfirstlane_b32 s6, v148
	buffer_load_dwordx4 v136, s[68:71], s3 offen lds
	s_add_i32 s3, s3, s8
	s_mov_b32 m0, s6
	v_add_u32_e32 v149, 0x8000, v137
	buffer_load_dwordx4 v136, s[68:71], s3 offen lds
	s_or_b32 s3, s11, 0x80
	v_readfirstlane_b32 s11, v149
	v_add_u32_e32 v150, 0xa000, v137
	s_mov_b32 s6, s70
	s_mov_b32 s7, s71
	s_mov_b32 m0, s11
	v_readfirstlane_b32 s11, v150
	buffer_load_dwordx4 v136, s[4:7], s3 offen lds
	s_add_i32 s3, s3, s8
	s_mov_b32 m0, s11
	v_add_u32_e32 v152, 0x1c000, v137
	buffer_load_dwordx4 v136, s[4:7], s3 offen lds
	s_or_b32 s3, s10, 0x80
	v_readfirstlane_b32 s10, v152
	v_add_u32_e32 v154, 0x1e000, v137
	s_mov_b32 m0, s10
	v_readfirstlane_b32 s10, v154
	buffer_load_dwordx4 v136, s[68:71], s3 offen lds
	s_add_i32 s3, s3, s8
	s_mov_b32 m0, s10
	v_and_b32_e32 v3, 15, v0
	buffer_load_dwordx4 v136, s[68:71], s3 offen lds
	v_cmp_eq_u32_e32 vcc, 1, v2
	s_and_saveexec_b64 s[98:99], vcc
	s_cbranch_execz .LBB0_539
	s_barrier
; #define WAIT_V(n) asm volatile("s_waitcnt vmcnt(" #n ")" ::: "memory")
; #define BAR __builtin_amdgcn_s_barrier()
; template <int MODE>
; __device__ __forceinline__ void gemm_tile(const int ph, const int which, const int pm, const int pn) {
;     ...
;   f32x4 acc[2][2][4][2] = {};
;   bf16x8 At[4][2], B0[2][2], B1[2][2];
;   const int nt = K / BK;
;     ...
;   if (wr == 1) BAR;
;   WAIT_V(4);
;   BAR;
;   STAGE(SB(1, 0), RB, bcol, 1);
;   STAGE(SA(1, 0), RA, brow, 1);
;   STAGE(SB(1, 1), RB, bcolB, 1);
;   WAIT_V(6);
;   BAR;
.LBB0_539:
	s_or_b64 exec, exec, s[98:99]
	s_waitcnt vmcnt(10)
	s_barrier
	v_and_b32_e32 v5, 48, v0
	v_lshlrev_b32_e32 v6, 6, v3
	v_lshlrev_b32_e32 v8, 2, v0
	v_or_b32_e32 v7, v6, v5
	v_and_b32_e32 v8, 32, v8
	s_mov_b32 s3, 0x10000
	v_bitop3_b32 v9, v7, s3, v8 bitop3:0xde
	s_mov_b32 s3, 0x14000
	v_bitop3_b32 v10, v7, s3, v8 bitop3:0xde
	s_mov_b32 s3, 0x18000
	v_lshl_or_b32 v131, v2, 6, v3
	v_lshlrev_b32_e32 v3, 13, v2
	v_lshlrev_b32_e32 v2, 6, v0
	v_bfe_u32 v130, v0, 6, 2
	v_bitop3_b32 v11, v7, s3, v8 bitop3:0xde
	s_mov_b32 s3, 0x1c000
	v_and_b32_e32 v2, 0x3c0, v2
	s_lshl_b32 s19, s20, 1
	s_lshl_b32 s11, s17, 1
	s_lshl_b32 s21, s22, 1
	s_lshr_b32 s2, s24, 6
	v_lshlrev_b32_e32 v4, 12, v130
	v_bitop3_b32 v6, v6, v8, v5 bitop3:0x36
	v_bitop3_b32 v7, v7, s3, v8 bitop3:0xde
	v_bitop3_b32 v5, v2, v8, v5 bitop3:0x36
	v_or_b32_e32 v8, 0x800, v3
	v_or_b32_e32 v12, 0x1000, v3
	v_or_b32_e32 v13, 0x1800, v3
	s_add_i32 s3, s19, 0x180
	s_lshl_b32 s23, s24, 1
	s_add_i32 s10, s20, 0x80
	s_addk_i32 s11, 0x80
	s_addk_i32 s19, 0x80
	s_addk_i32 s21, 0x80
	v_mov_b32_e32 v2, 0
	s_add_i32 s2, s2, -2
	v_add_u32_e32 v153, 0xc000, v137
	v_add_u32_e32 v151, 0xe000, v137
	s_mul_i32 s3, s24, s3
	s_mul_i32 s10, s23, s10
	s_mul_i32 s11, s24, s11
	s_mul_i32 s17, s23, s17
	s_mul_i32 s19, s24, s19
	s_mul_i32 s20, s23, s20
	s_mul_i32 s21, s24, s21
	s_mul_i32 s22, s23, s22
	s_mov_b32 s23, 0
	v_add_u32_e32 v156, v9, v4
	v_add_u32_e32 v135, v6, v3
	v_add_u32_e32 v134, v5, v8
	v_add_u32_e32 v133, v5, v12
	v_add_u32_e32 v132, v5, v13
	v_add_u32_e32 v155, v10, v4
	v_add_u32_e32 v144, v11, v4
	v_add_u32_e32 v138, v7, v4
	s_mov_b32 s25, 0
	v_mov_b32_e32 v3, v2
	v_mov_b32_e32 v4, v2
	v_mov_b32_e32 v5, v2
	v_mov_b32_e32 v6, v2
	v_mov_b32_e32 v7, v2
	v_mov_b32_e32 v8, v2
	v_mov_b32_e32 v9, v2
	v_mov_b32_e32 v10, v2
	v_mov_b32_e32 v11, v2
	v_mov_b32_e32 v12, v2
	v_mov_b32_e32 v13, v2
	v_mov_b32_e32 v14, v2
	v_mov_b32_e32 v15, v2
	v_mov_b32_e32 v16, v2
	v_mov_b32_e32 v17, v2
	v_mov_b32_e32 v18, v2
	v_mov_b32_e32 v19, v2
	v_mov_b32_e32 v20, v2
	v_mov_b32_e32 v21, v2
	v_mov_b32_e32 v22, v2
	v_mov_b32_e32 v23, v2
	v_mov_b32_e32 v24, v2
	v_mov_b32_e32 v25, v2
	s_waitcnt vmcnt(18)
	v_mov_b32_e32 v26, v2
	v_mov_b32_e32 v27, v2
	v_mov_b32_e32 v28, v2
	v_mov_b32_e32 v29, v2
	s_waitcnt vmcnt(16)
	v_mov_b32_e32 v30, v2
	v_mov_b32_e32 v31, v2
	v_mov_b32_e32 v32, v2
	v_mov_b32_e32 v33, v2
	s_waitcnt vmcnt(14)
	v_mov_b32_e32 v34, v2
	v_mov_b32_e32 v35, v2
	v_mov_b32_e32 v36, v2
	v_mov_b32_e32 v37, v2
	v_mov_b32_e32 v38, v2
	v_mov_b32_e32 v39, v2
	v_mov_b32_e32 v40, v2
	v_mov_b32_e32 v41, v2
	v_mov_b32_e32 v42, v2
	v_mov_b32_e32 v43, v2
	v_mov_b32_e32 v44, v2
	v_mov_b32_e32 v45, v2
	v_mov_b32_e32 v46, v2
	v_mov_b32_e32 v47, v2
	v_mov_b32_e32 v48, v2
	v_mov_b32_e32 v49, v2
	v_mov_b32_e32 v50, v2
	v_mov_b32_e32 v51, v2
	v_mov_b32_e32 v52, v2
	v_mov_b32_e32 v53, v2
	v_mov_b32_e32 v54, v2
	v_mov_b32_e32 v55, v2
	v_mov_b32_e32 v56, v2
	v_mov_b32_e32 v57, v2
	v_mov_b32_e32 v58, v2
	v_mov_b32_e32 v59, v2
	v_mov_b32_e32 v60, v2
	v_mov_b32_e32 v61, v2
	v_mov_b32_e32 v62, v2
	v_mov_b32_e32 v63, v2
	v_mov_b32_e32 v64, v2
	v_mov_b32_e32 v65, v2
	v_mov_b32_e32 v66, v2
	v_mov_b32_e32 v67, v2
	v_mov_b32_e32 v68, v2
	v_mov_b32_e32 v69, v2
	v_mov_b32_e32 v70, v2
	v_mov_b32_e32 v71, v2
	v_mov_b32_e32 v72, v2
	v_mov_b32_e32 v73, v2
	v_mov_b32_e32 v74, v2
	v_mov_b32_e32 v75, v2
	v_mov_b32_e32 v76, v2
	v_mov_b32_e32 v77, v2
	v_mov_b32_e32 v78, v2
	v_mov_b32_e32 v79, v2
	v_mov_b32_e32 v80, v2
	v_mov_b32_e32 v81, v2
	v_mov_b32_e32 v82, v2
	v_mov_b32_e32 v83, v2
	v_mov_b32_e32 v84, v2
	v_mov_b32_e32 v85, v2
	v_mov_b32_e32 v86, v2
	v_mov_b32_e32 v87, v2
	v_mov_b32_e32 v88, v2
	v_mov_b32_e32 v89, v2
	v_mov_b32_e32 v90, v2
	v_mov_b32_e32 v91, v2
	v_mov_b32_e32 v92, v2
	v_mov_b32_e32 v93, v2
	v_mov_b32_e32 v94, v2
	v_mov_b32_e32 v95, v2
	v_mov_b32_e32 v96, v2
	v_mov_b32_e32 v97, v2
	v_mov_b32_e32 v98, v2
	v_mov_b32_e32 v99, v2
	v_mov_b32_e32 v100, v2
	v_mov_b32_e32 v101, v2
	v_mov_b32_e32 v102, v2
	v_mov_b32_e32 v103, v2
	v_mov_b32_e32 v104, v2
	v_mov_b32_e32 v105, v2
	v_mov_b32_e32 v106, v2
	v_mov_b32_e32 v107, v2
	v_mov_b32_e32 v108, v2
	v_mov_b32_e32 v109, v2
	v_mov_b32_e32 v110, v2
	v_mov_b32_e32 v111, v2
	v_mov_b32_e32 v112, v2
	v_mov_b32_e32 v113, v2
	v_mov_b32_e32 v114, v2
	v_mov_b32_e32 v115, v2
	v_mov_b32_e32 v116, v2
	v_mov_b32_e32 v117, v2
	v_mov_b32_e32 v118, v2
	v_mov_b32_e32 v119, v2
	v_mov_b32_e32 v120, v2
	v_mov_b32_e32 v121, v2
	v_mov_b32_e32 v122, v2
	v_mov_b32_e32 v123, v2
	v_mov_b32_e32 v124, v2
	v_mov_b32_e32 v125, v2
	v_mov_b32_e32 v126, v2
	v_mov_b32_e32 v127, v2
	v_mov_b32_e32 v128, v2
	v_mov_b32_e32 v129, v2
	s_waitcnt vmcnt(6)

; __global__ void __launch_bounds__(512) mega_kernel(Params p) {
	.amdhsa_kernel _Z11mega_kernel6Params
		.amdhsa_group_segment_fixed_size 151552
		.amdhsa_private_segment_fixed_size 0
		.amdhsa_kernarg_size 528
		.amdhsa_user_sgpr_count 2
		.amdhsa_user_sgpr_dispatch_ptr 0
		.amdhsa_user_sgpr_queue_ptr 0
		.amdhsa_user_sgpr_kernarg_segment_ptr 1
		.amdhsa_user_sgpr_dispatch_id 0
		.amdhsa_user_sgpr_kernarg_preload_length 0
		.amdhsa_user_sgpr_kernarg_preload_offset 0
		.amdhsa_user_sgpr_private_segment_size 0
		.amdhsa_uses_dynamic_stack 0
		.amdhsa_enable_private_segment 0
		.amdhsa_system_sgpr_workgroup_id_x 1
		.amdhsa_system_sgpr_workgroup_id_y 0
		.amdhsa_system_sgpr_workgroup_id_z 0
		.amdhsa_system_sgpr_workgroup_info 0
		.amdhsa_system_vgpr_workitem_id 2
		.amdhsa_next_free_vgpr 256
		.amdhsa_next_free_sgpr 100
		.amdhsa_accum_offset 256
		.amdhsa_reserve_vcc 1
		.amdhsa_float_round_mode_32 0
		.amdhsa_float_round_mode_16_64 0
		.amdhsa_float_denorm_mode_32 3
		.amdhsa_float_denorm_mode_16_64 3
		.amdhsa_dx10_clamp 1
		.amdhsa_ieee_mode 1
		.amdhsa_fp16_overflow 0
		.amdhsa_tg_split 0
		.amdhsa_exception_fp_ieee_invalid_op 0
		.amdhsa_exception_fp_denorm_src 0
		.amdhsa_exception_fp_ieee_div_zero 0
		.amdhsa_exception_fp_ieee_overflow 0
		.amdhsa_exception_fp_ieee_underflow 0
		.amdhsa_exception_fp_ieee_inexact 0
		.amdhsa_exception_int_div_zero 0
	.end_amdhsa_kernel

; __global__ void __launch_bounds__(512) mega_kernel(Params p) {
amdhsa.kernels:
  - .agpr_count:     0
    .args:
      - .offset:         0
        .size:           272
        .value_kind:     by_value
      - .offset:         272
        .size:           4
        .value_kind:     hidden_block_count_x
      - .offset:         276
        .size:           4
        .value_kind:     hidden_block_count_y
      - .offset:         280
        .size:           4
        .value_kind:     hidden_block_count_z
      - .offset:         284
        .size:           2
        .value_kind:     hidden_group_size_x
      - .offset:         286
        .size:           2
        .value_kind:     hidden_group_size_y
      - .offset:         288
        .size:           2
        .value_kind:     hidden_group_size_z
      - .offset:         290
        .size:           2
        .value_kind:     hidden_remainder_x
      - .offset:         292
        .size:           2
        .value_kind:     hidden_remainder_y
      - .offset:         294
        .size:           2
        .value_kind:     hidden_remainder_z
      - .offset:         312
        .size:           8
        .value_kind:     hidden_global_offset_x
      - .offset:         320
        .size:           8
        .value_kind:     hidden_global_offset_y
      - .offset:         328
        .size:           8
        .value_kind:     hidden_global_offset_z
      - .offset:         336
        .size:           2
        .value_kind:     hidden_grid_dims
      - .offset:         360
        .size:           8
        .value_kind:     hidden_multigrid_sync_arg
    .group_segment_fixed_size: 151552
    .kernarg_segment_align: 8
    .kernarg_segment_size: 528
    .language:       OpenCL C
    .language_version:
      - 2
      - 0
    .max_flat_workgroup_size: 512
    .name:           _Z11mega_kernel6Params
    .private_segment_fixed_size: 0
    .sgpr_count:     106
    .sgpr_spill_count: 98
    .symbol:         _Z11mega_kernel6Params.kd
    .uniform_work_group_size: 1
    .uses_dynamic_stack: false
    .vgpr_count:     256
    .vgpr_spill_count: 0
    .wavefront_size: 64
